# v13 + SwiGLU epilogue: row rstd for all 8 row groups computed in one batched pass (8 bpermutes in flight instead of 16 serialized round trips)
# baseline (speedup 1.0000x reference)
; __device__ __forceinline__ float rstd_row4(const float* ssrow, int fq) { const f32x4 a = *(const f32x4*)(ssrow + 4 * fq); float ss = (a[0] + a[1]) + (a[2] + a[3]);
;     ss += __shfl_xor(ss, 16); ss += __shfl_xor(ss, 32); return __builtin_amdgcn_rsqf(ss * (1.0f / 1024.0f) + 1e-6f); }
;     __device__ __forceinline__ void operator()(const f32x4 (&acc)[2][2][4][2], const Unit& u, int wr, int wc, int fr, int fq) const {
; #pragma unroll
;         for (int ai = 0; ai < 2; ++ai)
; #pragma unroll
;             for (int m = 0; m < 4; ++m) {
;                 const int row = u.pm * BM + ai * HALF + wr * 64 + m * 16 + fr; const float rs = rstd_row4(ss + (size_t)row * 16, fq);
;                 bf16_t* rowp = out + (size_t)row * 2816 + u.pn * 128 + wc * 32 + fq * 8;
;                 u32x4 w;
;                 const float rsl = rs * (-1.4426950408889634f), rs2 = rs * rs;
; #pragma unroll
;                 for (int n = 0; n < 2; ++n) {
;                     const f32x4 ta = acc[ai][0][m][n] * rsl, gu = acc[ai][0][m][n] * acc[ai][1][m][n]; f32x4 t;
.LBB0_185:
	s_lshl_b32 s13, s28, 8
	v_add_u32_e32 v156, s13, v158
	v_ashrrev_i32_e32 v157, 31, v156
	v_lshlrev_b64 v[142:143], 6, v[156:157]
	v_lshl_add_u64 v[142:143], v[136:137], 0, v[142:143]
	global_load_dwordx4 v[164:167], v[142:143], off
	global_load_dwordx4 v[176:179], v[142:143], off offset:1024
	global_load_dwordx4 v[180:183], v[142:143], off offset:2048
	global_load_dwordx4 v[184:187], v[142:143], off offset:3072
	v_lshl_add_u64 v[216:217], v[150:151], 4, v[142:143]
	global_load_dwordx4 v[188:191], v[216:217], off
	global_load_dwordx4 v[192:195], v[216:217], off offset:1024
	global_load_dwordx4 v[196:199], v[216:217], off offset:2048
	global_load_dwordx4 v[220:223], v[216:217], off offset:3072
	v_and_b32_e32 v170, 64, v203
	v_xor_b32_e32 v157, 16, v203
	v_pk_mul_f32 v[168:169], v[112:113], v[120:121]
	v_add_u32_e32 v120, 64, v170
	v_cmp_lt_i32_e32 vcc, v157, v120
	v_xor_b32_e32 v171, 32, v203
	v_pk_mul_f32 v[126:127], v[118:119], v[126:127]
	v_cndmask_b32_e32 v121, v203, v157, vcc
	v_lshlrev_b32_e32 v121, 2, v121
	v_cmp_lt_i32_e32 vcc, v171, v120
	v_pk_mul_f32 v[124:125], v[116:117], v[124:125]
	v_pk_mul_f32 v[122:123], v[114:115], v[122:123]
	v_cndmask_b32_e32 v120, v203, v171, vcc
	v_lshlrev_b32_e32 v120, 2, v120
	s_lshl_b32 s28, s29, 7
	v_mov_b64_e32 v[142:143], s[80:81]
	s_ashr_i32 s29, s28, 31
	s_lshl_b64 s[28:29], s[28:29], 1
	v_add_u32_e32 v170, s13, v160
	v_ashrrev_i32_e32 v171, 31, v170
	v_pk_mul_f32 v[110:111], v[102:103], v[110:111]
	v_pk_mul_f32 v[108:109], v[100:101], v[108:109]
	v_pk_mul_f32 v[106:107], v[98:99], v[106:107]
	v_pk_mul_f32 v[104:105], v[96:97], v[104:105]
	v_pk_mul_f32 v[94:95], v[86:87], v[94:95]
	v_pk_mul_f32 v[92:93], v[84:85], v[92:93]
	v_pk_mul_f32 v[90:91], v[82:83], v[90:91]
	v_pk_mul_f32 v[88:89], v[80:81], v[88:89]
	v_pk_mul_f32 v[78:79], v[70:71], v[78:79]
	v_pk_mul_f32 v[76:77], v[68:69], v[76:77]
	v_pk_mul_f32 v[74:75], v[66:67], v[74:75]
	v_pk_mul_f32 v[72:73], v[64:65], v[72:73]
	v_pk_mul_f32 v[62:63], v[54:55], v[62:63]
	v_pk_mul_f32 v[60:61], v[52:53], v[60:61]
	v_pk_mul_f32 v[58:59], v[50:51], v[58:59]
	v_pk_mul_f32 v[56:57], v[48:49], v[56:57]
	v_pk_mul_f32 v[46:47], v[38:39], v[46:47]
	v_pk_mul_f32 v[44:45], v[36:37], v[44:45]
	v_pk_mul_f32 v[42:43], v[34:35], v[42:43]
	v_pk_mul_f32 v[40:41], v[32:33], v[40:41]
	v_pk_mul_f32 v[30:31], v[22:23], v[30:31]
	v_pk_mul_f32 v[28:29], v[20:21], v[28:29]
	v_pk_mul_f32 v[26:27], v[18:19], v[26:27]
	v_pk_mul_f32 v[24:25], v[16:17], v[24:25]
	v_pk_mul_f32 v[14:15], v[6:7], v[14:15]
	v_pk_mul_f32 v[12:13], v[4:5], v[12:13]
	v_pk_mul_f32 v[10:11], v[2:3], v[10:11]
	v_pk_mul_f32 v[8:9], v[0:1], v[8:9]
	s_andn2_b64 vcc, exec, s[36:37]
	s_waitcnt vmcnt(0)
	v_add_f32_e32 v232, v164, v165
	v_add_f32_e32 v233, v166, v167
	v_add_f32_e32 v224, v232, v233
	v_add_f32_e32 v232, v176, v177
	v_add_f32_e32 v233, v178, v179
	v_add_f32_e32 v225, v232, v233
	v_add_f32_e32 v232, v180, v181
	v_add_f32_e32 v233, v182, v183
	v_add_f32_e32 v226, v232, v233
	v_add_f32_e32 v232, v184, v185
	v_add_f32_e32 v233, v186, v187
	v_add_f32_e32 v227, v232, v233
	v_add_f32_e32 v232, v188, v189
	v_add_f32_e32 v233, v190, v191
	v_add_f32_e32 v228, v232, v233
	v_add_f32_e32 v232, v192, v193
	v_add_f32_e32 v233, v194, v195
	v_add_f32_e32 v229, v232, v233
	v_add_f32_e32 v232, v196, v197
	v_add_f32_e32 v233, v198, v199
	v_add_f32_e32 v230, v232, v233
	v_add_f32_e32 v232, v220, v221
	v_add_f32_e32 v233, v222, v223
	v_add_f32_e32 v231, v232, v233
	ds_bpermute_b32 v240, v121, v224
	ds_bpermute_b32 v241, v121, v225
	ds_bpermute_b32 v242, v121, v226
	ds_bpermute_b32 v243, v121, v227
	ds_bpermute_b32 v244, v121, v228
	ds_bpermute_b32 v245, v121, v229
	ds_bpermute_b32 v246, v121, v230
	ds_bpermute_b32 v247, v121, v231
	s_waitcnt lgkmcnt(0)
	v_add_f32_e32 v224, v224, v240
	v_add_f32_e32 v225, v225, v241
	v_add_f32_e32 v226, v226, v242
	v_add_f32_e32 v227, v227, v243
	v_add_f32_e32 v228, v228, v244
	v_add_f32_e32 v229, v229, v245
	v_add_f32_e32 v230, v230, v246
	v_add_f32_e32 v231, v231, v247
	ds_bpermute_b32 v240, v120, v224
	ds_bpermute_b32 v241, v120, v225
	ds_bpermute_b32 v242, v120, v226
	ds_bpermute_b32 v243, v120, v227
	ds_bpermute_b32 v244, v120, v228
	ds_bpermute_b32 v245, v120, v229
	ds_bpermute_b32 v246, v120, v230
	ds_bpermute_b32 v247, v120, v231
	s_waitcnt lgkmcnt(0)
; __device__ __forceinline__ u32x2 pack4(f32x4 v) { u32x2 w; w.x = cvt_pk_bf16(v[0], v[1]); w.y = cvt_pk_bf16(v[2], v[3]); return w; }
; __device__ __forceinline__ float rstd_row4(const float* ssrow, int fq) { const f32x4 a = *(const f32x4*)(ssrow + 4 * fq); float ss = (a[0] + a[1]) + (a[2] + a[3]);
;     ss += __shfl_xor(ss, 16); ss += __shfl_xor(ss, 32); return __builtin_amdgcn_rsqf(ss * (1.0f / 1024.0f) + 1e-6f); }
;     __device__ __forceinline__ void operator()(const f32x4 (&acc)[2][2][4][2], const Unit& u, int wr, int wc, int fr, int fq) const {
;     ...
;             for (int m = 0; m < 4; ++m) {
;                 const int row = u.pm * BM + ai * HALF + wr * 64 + m * 16 + fr; const float rs = rstd_row4(ss + (size_t)row * 16, fq);
;                 bf16_t* rowp = out + (size_t)row * 2816 + u.pn * 128 + wc * 32 + fq * 8;
;                 u32x4 w;
;                 const float rsl = rs * (-1.4426950408889634f), rs2 = rs * rs;
; #pragma unroll
;                 for (int n = 0; n < 2; ++n) {
;                     const f32x4 ta = acc[ai][0][m][n] * rsl, gu = acc[ai][0][m][n] * acc[ai][1][m][n]; f32x4 t;
;                     t[0] = __builtin_amdgcn_exp2f(ta[0]); t[1] = __builtin_amdgcn_exp2f(ta[1]); t[2] = __builtin_amdgcn_exp2f(ta[2]); t[3] = __builtin_amdgcn_exp2f(ta[3]);
;                     const f32x4 dn = t + 1.0f; f32x4 r;
;                     r[0] = __builtin_amdgcn_rcpf(dn[0]); r[1] = __builtin_amdgcn_rcpf(dn[1]); r[2] = __builtin_amdgcn_rcpf(dn[2]); r[3] = __builtin_amdgcn_rcpf(dn[3]);
;                     const f32x4 h = gu * (r * rs2);
;                     const u32x2 pk = pack4(h); if (n == 0) { w.x = pk.x; w.y = pk.y; } else { w.z = pk.x; w.w = pk.y; } }
;                 *(u32x4*)rowp = w;
	v_add_f32_e32 v224, v224, v240
	v_add_f32_e32 v225, v225, v241
	v_add_f32_e32 v226, v226, v242
	v_add_f32_e32 v227, v227, v243
	v_add_f32_e32 v228, v228, v244
	v_add_f32_e32 v229, v229, v245
	v_add_f32_e32 v230, v230, v246
	v_add_f32_e32 v231, v231, v247
	v_fmamk_f32 v224, v224, 0x3a800000, v201
	v_fmamk_f32 v225, v225, 0x3a800000, v201
	v_fmamk_f32 v226, v226, 0x3a800000, v201
	v_fmamk_f32 v227, v227, 0x3a800000, v201
	v_fmamk_f32 v228, v228, 0x3a800000, v201
	v_fmamk_f32 v229, v229, 0x3a800000, v201
	v_fmamk_f32 v230, v230, 0x3a800000, v201
	v_fmamk_f32 v231, v231, 0x3a800000, v201
	v_rsq_f32_e32 v224, v224
	v_rsq_f32_e32 v225, v225
	v_rsq_f32_e32 v226, v226
	v_rsq_f32_e32 v227, v227
	v_rsq_f32_e32 v228, v228
	v_rsq_f32_e32 v229, v229
	v_rsq_f32_e32 v230, v230
	v_rsq_f32_e32 v231, v231
	v_mad_i64_i32 v[164:165], s[38:39], v156, s94, v[142:143]
	v_lshl_add_u64 v[164:165], v[164:165], 0, s[28:29]
	v_lshl_add_u64 v[164:165], v[164:165], 0, s[4:5]
	v_lshlrev_b64 v[166:167], 6, v[170:171]
	v_lshl_add_u64 v[164:165], v[164:165], 0, v[144:145]
	v_lshl_add_u64 v[166:167], v[136:137], 0, v[166:167]
	v_mov_b32_e32 v157, v224
	s_nop 0
	v_mul_f32_e32 v172, 0xbfb8aa3b, v157
	v_pk_mul_f32 v[118:119], v[118:119], v[172:173] op_sel_hi:[1,0]
	v_pk_mul_f32 v[116:117], v[116:117], v[172:173] op_sel_hi:[1,0]
	v_pk_mul_f32 v[114:115], v[114:115], v[172:173] op_sel_hi:[1,0]
	v_pk_mul_f32 v[112:113], v[112:113], v[172:173] op_sel_hi:[1,0]
	v_exp_f32_e32 v116, v116
	v_exp_f32_e32 v117, v117
	v_exp_f32_e32 v118, v118
	v_exp_f32_e32 v119, v119
	v_exp_f32_e32 v112, v112
	v_exp_f32_e32 v114, v114
	v_exp_f32_e32 v115, v115
	v_exp_f32_e32 v113, v113
	v_pk_add_f32 v[118:119], v[118:119], 1.0 op_sel_hi:[1,0]
	v_pk_add_f32 v[116:117], v[116:117], 1.0 op_sel_hi:[1,0]
	v_pk_add_f32 v[114:115], v[114:115], 1.0 op_sel_hi:[1,0]
	v_pk_add_f32 v[112:113], v[112:113], 1.0 op_sel_hi:[1,0]
	v_rcp_f32_e32 v116, v116
	v_rcp_f32_e32 v117, v117
	v_rcp_f32_e32 v118, v118
	v_rcp_f32_e32 v119, v119
	v_rcp_f32_e32 v112, v112
	v_rcp_f32_e32 v113, v113
	v_rcp_f32_e32 v114, v114
	v_rcp_f32_e32 v115, v115
	v_mul_f32_e32 v174, v157, v157
	v_pk_mul_f32 v[116:117], v[174:175], v[116:117] op_sel_hi:[0,1]
	v_pk_mul_f32 v[118:119], v[174:175], v[118:119] op_sel_hi:[0,1]
	v_pk_mul_f32 v[112:113], v[174:175], v[112:113] op_sel_hi:[0,1]
	v_pk_mul_f32 v[114:115], v[174:175], v[114:115] op_sel_hi:[0,1]
	v_pk_mul_f32 v[118:119], v[126:127], v[118:119]
	v_pk_mul_f32 v[116:117], v[124:125], v[116:117]
	v_pk_mul_f32 v[122:123], v[122:123], v[114:115]
	v_pk_mul_f32 v[114:115], v[168:169], v[112:113]
	v_cvt_pk_bf16_f32 v112, v116, v117
	v_cvt_pk_bf16_f32 v113, v118, v119
	v_cvt_pk_bf16_f32 v114, v114, v115
	v_cvt_pk_bf16_f32 v115, v122, v123
	global_store_dwordx4 v[164:165], v[112:115], off
	s_nop 1
	v_add_u32_e32 v112, s13, v161
	v_ashrrev_i32_e32 v113, 31, v112
	v_lshlrev_b64 v[116:117], 6, v[112:113]
	v_mad_i64_i32 v[114:115], s[38:39], v170, s94, v[142:143]
	v_mov_b32_e32 v113, v225
	v_lshl_add_u64 v[114:115], v[114:115], 0, s[28:29]
	v_lshl_add_u64 v[114:115], v[114:115], 0, s[4:5]
	v_lshl_add_u64 v[114:115], v[114:115], 0, v[144:145]
	v_mul_f32_e32 v118, 0xbfb8aa3b, v113
	v_pk_mul_f32 v[102:103], v[102:103], v[118:119] op_sel_hi:[1,0]
	v_pk_mul_f32 v[100:101], v[100:101], v[118:119] op_sel_hi:[1,0]
	v_pk_mul_f32 v[98:99], v[98:99], v[118:119] op_sel_hi:[1,0]
	v_pk_mul_f32 v[96:97], v[96:97], v[118:119] op_sel_hi:[1,0]
	v_exp_f32_e32 v100, v100
	v_exp_f32_e32 v101, v101
	v_exp_f32_e32 v102, v102
	v_exp_f32_e32 v103, v103
	v_exp_f32_e32 v96, v96
	v_exp_f32_e32 v98, v98
	v_exp_f32_e32 v99, v99
	v_exp_f32_e32 v97, v97
	v_pk_add_f32 v[102:103], v[102:103], 1.0 op_sel_hi:[1,0]
	v_pk_add_f32 v[100:101], v[100:101], 1.0 op_sel_hi:[1,0]
	v_pk_add_f32 v[98:99], v[98:99], 1.0 op_sel_hi:[1,0]
	v_pk_add_f32 v[96:97], v[96:97], 1.0 op_sel_hi:[1,0]
	v_rcp_f32_e32 v100, v100
	v_rcp_f32_e32 v101, v101
	v_rcp_f32_e32 v102, v102
	v_rcp_f32_e32 v103, v103
	v_rcp_f32_e32 v96, v96
	v_rcp_f32_e32 v97, v97
	v_rcp_f32_e32 v98, v98
	v_rcp_f32_e32 v99, v99
	v_mul_f32_e32 v122, v113, v113
	v_pk_mul_f32 v[100:101], v[122:123], v[100:101] op_sel_hi:[0,1]
	v_pk_mul_f32 v[102:103], v[122:123], v[102:103] op_sel_hi:[0,1]
	v_pk_mul_f32 v[96:97], v[122:123], v[96:97] op_sel_hi:[0,1]
	v_pk_mul_f32 v[98:99], v[122:123], v[98:99] op_sel_hi:[0,1]
	v_pk_mul_f32 v[102:103], v[110:111], v[102:103]
	v_pk_mul_f32 v[100:101], v[108:109], v[100:101]
	v_pk_mul_f32 v[106:107], v[106:107], v[98:99]
	v_pk_mul_f32 v[98:99], v[104:105], v[96:97]
	v_cvt_pk_bf16_f32 v96, v100, v101
	v_cvt_pk_bf16_f32 v97, v102, v103
	v_cvt_pk_bf16_f32 v98, v98, v99
	v_cvt_pk_bf16_f32 v99, v106, v107
	v_lshl_add_u64 v[116:117], v[136:137], 0, v[116:117]
	global_store_dwordx4 v[114:115], v[96:99], off
	s_nop 1
	v_add_u32_e32 v96, s13, v162
	v_ashrrev_i32_e32 v97, 31, v96
	v_lshlrev_b64 v[100:101], 6, v[96:97]
	v_mad_i64_i32 v[98:99], s[38:39], v112, s94, v[142:143]
	v_mov_b32_e32 v97, v226
	v_lshl_add_u64 v[98:99], v[98:99], 0, s[28:29]
	v_lshl_add_u64 v[98:99], v[98:99], 0, s[4:5]
	v_lshl_add_u64 v[98:99], v[98:99], 0, v[144:145]
	v_mul_f32_e32 v102, 0xbfb8aa3b, v97
	v_pk_mul_f32 v[86:87], v[86:87], v[102:103] op_sel_hi:[1,0]
	v_pk_mul_f32 v[84:85], v[84:85], v[102:103] op_sel_hi:[1,0]
	v_pk_mul_f32 v[82:83], v[82:83], v[102:103] op_sel_hi:[1,0]
	v_pk_mul_f32 v[80:81], v[80:81], v[102:103] op_sel_hi:[1,0]
	v_exp_f32_e32 v84, v84
	v_exp_f32_e32 v85, v85
	v_exp_f32_e32 v86, v86
	v_exp_f32_e32 v87, v87
	v_exp_f32_e32 v80, v80
	v_exp_f32_e32 v82, v82
	v_exp_f32_e32 v83, v83
	v_exp_f32_e32 v81, v81
	v_pk_add_f32 v[86:87], v[86:87], 1.0 op_sel_hi:[1,0]
; __device__ __forceinline__ u32x2 pack4(f32x4 v) { u32x2 w; w.x = cvt_pk_bf16(v[0], v[1]); w.y = cvt_pk_bf16(v[2], v[3]); return w; }
;     __device__ __forceinline__ void operator()(const f32x4 (&acc)[2][2][4][2], const Unit& u, int wr, int wc, int fr, int fq) const {
;     ...
;             for (int m = 0; m < 4; ++m) {
;                 const int row = u.pm * BM + ai * HALF + wr * 64 + m * 16 + fr; const float rs = rstd_row4(ss + (size_t)row * 16, fq);
;                 bf16_t* rowp = out + (size_t)row * 2816 + u.pn * 128 + wc * 32 + fq * 8;
;                 u32x4 w;
;                 const float rsl = rs * (-1.4426950408889634f), rs2 = rs * rs;
; #pragma unroll
;                 for (int n = 0; n < 2; ++n) {
;                     const f32x4 ta = acc[ai][0][m][n] * rsl, gu = acc[ai][0][m][n] * acc[ai][1][m][n]; f32x4 t;
;                     t[0] = __builtin_amdgcn_exp2f(ta[0]); t[1] = __builtin_amdgcn_exp2f(ta[1]); t[2] = __builtin_amdgcn_exp2f(ta[2]); t[3] = __builtin_amdgcn_exp2f(ta[3]);
;                     const f32x4 dn = t + 1.0f; f32x4 r;
;                     r[0] = __builtin_amdgcn_rcpf(dn[0]); r[1] = __builtin_amdgcn_rcpf(dn[1]); r[2] = __builtin_amdgcn_rcpf(dn[2]); r[3] = __builtin_amdgcn_rcpf(dn[3]);
;                     const f32x4 h = gu * (r * rs2);
;                     const u32x2 pk = pack4(h); if (n == 0) { w.x = pk.x; w.y = pk.y; } else { w.z = pk.x; w.w = pk.y; } }
;                 *(u32x4*)rowp = w;
	v_pk_add_f32 v[84:85], v[84:85], 1.0 op_sel_hi:[1,0]
	v_pk_add_f32 v[82:83], v[82:83], 1.0 op_sel_hi:[1,0]
	v_pk_add_f32 v[80:81], v[80:81], 1.0 op_sel_hi:[1,0]
	v_rcp_f32_e32 v84, v84
	v_rcp_f32_e32 v85, v85
	v_rcp_f32_e32 v86, v86
	v_rcp_f32_e32 v87, v87
	v_rcp_f32_e32 v80, v80
	v_rcp_f32_e32 v81, v81
	v_rcp_f32_e32 v82, v82
	v_rcp_f32_e32 v83, v83
	v_mul_f32_e32 v104, v97, v97
	v_pk_mul_f32 v[84:85], v[104:105], v[84:85] op_sel_hi:[0,1]
	v_pk_mul_f32 v[86:87], v[104:105], v[86:87] op_sel_hi:[0,1]
	v_pk_mul_f32 v[80:81], v[104:105], v[80:81] op_sel_hi:[0,1]
	v_pk_mul_f32 v[82:83], v[104:105], v[82:83] op_sel_hi:[0,1]
	v_pk_mul_f32 v[86:87], v[94:95], v[86:87]
	v_pk_mul_f32 v[84:85], v[92:93], v[84:85]
	v_pk_mul_f32 v[90:91], v[90:91], v[82:83]
	v_pk_mul_f32 v[82:83], v[88:89], v[80:81]
	v_cvt_pk_bf16_f32 v80, v84, v85
	v_cvt_pk_bf16_f32 v81, v86, v87
	v_cvt_pk_bf16_f32 v82, v82, v83
	v_cvt_pk_bf16_f32 v83, v90, v91
	v_lshl_add_u64 v[100:101], v[136:137], 0, v[100:101]
	global_store_dwordx4 v[98:99], v[80:83], off
	s_nop 1
	v_mad_i64_i32 v[80:81], s[38:39], v96, s94, v[142:143]
	v_lshl_add_u64 v[80:81], v[80:81], 0, s[28:29]
	v_lshl_add_u64 v[80:81], v[80:81], 0, s[4:5]
	v_add_u32_e32 v82, 0x80, v156
	v_ashrrev_i32_e32 v83, 31, v82
	v_lshl_add_u64 v[80:81], v[80:81], 0, v[144:145]
	v_mov_b32_e32 v87, v227
	v_lshlrev_b64 v[84:85], 6, v[82:83]
	v_lshl_add_u64 v[84:85], v[136:137], 0, v[84:85]
	v_mul_f32_e32 v86, 0xbfb8aa3b, v87
	v_pk_mul_f32 v[70:71], v[70:71], v[86:87] op_sel_hi:[1,0]
	v_pk_mul_f32 v[68:69], v[68:69], v[86:87] op_sel_hi:[1,0]
	v_pk_mul_f32 v[66:67], v[66:67], v[86:87] op_sel_hi:[1,0]
	v_pk_mul_f32 v[64:65], v[64:65], v[86:87] op_sel_hi:[1,0]
	v_exp_f32_e32 v68, v68
	v_exp_f32_e32 v69, v69
	v_exp_f32_e32 v70, v70
	v_exp_f32_e32 v71, v71
	v_exp_f32_e32 v64, v64
	v_exp_f32_e32 v66, v66
	v_exp_f32_e32 v67, v67
	v_exp_f32_e32 v65, v65
	v_pk_add_f32 v[70:71], v[70:71], 1.0 op_sel_hi:[1,0]
	v_pk_add_f32 v[68:69], v[68:69], 1.0 op_sel_hi:[1,0]
	v_pk_add_f32 v[66:67], v[66:67], 1.0 op_sel_hi:[1,0]
	v_pk_add_f32 v[64:65], v[64:65], 1.0 op_sel_hi:[1,0]
	v_rcp_f32_e32 v68, v68
	v_rcp_f32_e32 v69, v69
	v_rcp_f32_e32 v70, v70
	v_rcp_f32_e32 v71, v71
	v_rcp_f32_e32 v64, v64
	v_rcp_f32_e32 v65, v65
	v_rcp_f32_e32 v66, v66
	v_rcp_f32_e32 v67, v67
	v_mul_f32_e32 v88, v87, v87
	v_pk_mul_f32 v[68:69], v[88:89], v[68:69] op_sel_hi:[0,1]
	v_pk_mul_f32 v[70:71], v[88:89], v[70:71] op_sel_hi:[0,1]
	v_pk_mul_f32 v[64:65], v[88:89], v[64:65] op_sel_hi:[0,1]
	v_pk_mul_f32 v[66:67], v[88:89], v[66:67] op_sel_hi:[0,1]
	v_pk_mul_f32 v[70:71], v[78:79], v[70:71]
	v_pk_mul_f32 v[68:69], v[76:77], v[68:69]
	v_pk_mul_f32 v[74:75], v[74:75], v[66:67]
	v_pk_mul_f32 v[66:67], v[72:73], v[64:65]
	v_cvt_pk_bf16_f32 v64, v68, v69
	v_cvt_pk_bf16_f32 v65, v70, v71
	v_cvt_pk_bf16_f32 v66, v66, v67
	v_cvt_pk_bf16_f32 v67, v74, v75
	global_store_dwordx4 v[80:81], v[64:67], off
	s_nop 1
	v_add_u32_e32 v64, 0x90, v156
	v_ashrrev_i32_e32 v65, 31, v64
	v_lshlrev_b64 v[68:69], 6, v[64:65]
	v_mad_i64_i32 v[66:67], s[38:39], v82, s94, v[142:143]
	v_mov_b32_e32 v65, v228
	v_lshl_add_u64 v[66:67], v[66:67], 0, s[28:29]
	v_lshl_add_u64 v[66:67], v[66:67], 0, s[4:5]
	v_lshl_add_u64 v[66:67], v[66:67], 0, v[144:145]
	v_mul_f32_e32 v70, 0xbfb8aa3b, v65
	v_pk_mul_f32 v[54:55], v[54:55], v[70:71] op_sel_hi:[1,0]
	v_pk_mul_f32 v[52:53], v[52:53], v[70:71] op_sel_hi:[1,0]
	v_pk_mul_f32 v[50:51], v[50:51], v[70:71] op_sel_hi:[1,0]
	v_pk_mul_f32 v[48:49], v[48:49], v[70:71] op_sel_hi:[1,0]
	v_exp_f32_e32 v52, v52
	v_exp_f32_e32 v53, v53
	v_exp_f32_e32 v54, v54
	v_exp_f32_e32 v55, v55
	v_exp_f32_e32 v48, v48
	v_exp_f32_e32 v50, v50
	v_exp_f32_e32 v51, v51
	v_exp_f32_e32 v49, v49
	v_pk_add_f32 v[54:55], v[54:55], 1.0 op_sel_hi:[1,0]
	v_pk_add_f32 v[52:53], v[52:53], 1.0 op_sel_hi:[1,0]
	v_pk_add_f32 v[50:51], v[50:51], 1.0 op_sel_hi:[1,0]
	v_pk_add_f32 v[48:49], v[48:49], 1.0 op_sel_hi:[1,0]
	v_rcp_f32_e32 v52, v52
	v_rcp_f32_e32 v53, v53
	v_rcp_f32_e32 v54, v54
	v_rcp_f32_e32 v55, v55
	v_rcp_f32_e32 v48, v48
	v_rcp_f32_e32 v49, v49
	v_rcp_f32_e32 v50, v50
	v_rcp_f32_e32 v51, v51
	v_mul_f32_e32 v72, v65, v65
	v_pk_mul_f32 v[52:53], v[72:73], v[52:53] op_sel_hi:[0,1]
	v_pk_mul_f32 v[54:55], v[72:73], v[54:55] op_sel_hi:[0,1]
	v_pk_mul_f32 v[48:49], v[72:73], v[48:49] op_sel_hi:[0,1]
	v_pk_mul_f32 v[50:51], v[72:73], v[50:51] op_sel_hi:[0,1]
	v_pk_mul_f32 v[54:55], v[62:63], v[54:55]
	v_pk_mul_f32 v[52:53], v[60:61], v[52:53]
	v_pk_mul_f32 v[58:59], v[58:59], v[50:51]
	v_pk_mul_f32 v[50:51], v[56:57], v[48:49]
	v_cvt_pk_bf16_f32 v48, v52, v53
	v_cvt_pk_bf16_f32 v49, v54, v55
	v_cvt_pk_bf16_f32 v50, v50, v51
	v_cvt_pk_bf16_f32 v51, v58, v59
	v_lshl_add_u64 v[68:69], v[136:137], 0, v[68:69]
	global_store_dwordx4 v[66:67], v[48:51], off
	s_nop 1
	v_add_u32_e32 v48, 0xa0, v156
	v_ashrrev_i32_e32 v49, 31, v48
	v_lshlrev_b64 v[52:53], 6, v[48:49]
	v_mad_i64_i32 v[50:51], s[38:39], v64, s94, v[142:143]
	v_mov_b32_e32 v49, v229
	v_lshl_add_u64 v[50:51], v[50:51], 0, s[28:29]
	v_lshl_add_u64 v[50:51], v[50:51], 0, s[4:5]
	v_lshl_add_u64 v[50:51], v[50:51], 0, v[144:145]
	v_mul_f32_e32 v54, 0xbfb8aa3b, v49
; __device__ __forceinline__ u32x2 pack4(f32x4 v) { u32x2 w; w.x = cvt_pk_bf16(v[0], v[1]); w.y = cvt_pk_bf16(v[2], v[3]); return w; }
;     __device__ __forceinline__ void operator()(const f32x4 (&acc)[2][2][4][2], const Unit& u, int wr, int wc, int fr, int fq) const {
;     ...
;             for (int m = 0; m < 4; ++m) {
;                 const int row = u.pm * BM + ai * HALF + wr * 64 + m * 16 + fr; const float rs = rstd_row4(ss + (size_t)row * 16, fq);
;                 bf16_t* rowp = out + (size_t)row * 2816 + u.pn * 128 + wc * 32 + fq * 8;
;                 u32x4 w;
;                 const float rsl = rs * (-1.4426950408889634f), rs2 = rs * rs;
; #pragma unroll
;                 for (int n = 0; n < 2; ++n) {
;                     const f32x4 ta = acc[ai][0][m][n] * rsl, gu = acc[ai][0][m][n] * acc[ai][1][m][n]; f32x4 t;
;                     t[0] = __builtin_amdgcn_exp2f(ta[0]); t[1] = __builtin_amdgcn_exp2f(ta[1]); t[2] = __builtin_amdgcn_exp2f(ta[2]); t[3] = __builtin_amdgcn_exp2f(ta[3]);
;                     const f32x4 dn = t + 1.0f; f32x4 r;
;                     r[0] = __builtin_amdgcn_rcpf(dn[0]); r[1] = __builtin_amdgcn_rcpf(dn[1]); r[2] = __builtin_amdgcn_rcpf(dn[2]); r[3] = __builtin_amdgcn_rcpf(dn[3]);
;                     const f32x4 h = gu * (r * rs2);
;                     const u32x2 pk = pack4(h); if (n == 0) { w.x = pk.x; w.y = pk.y; } else { w.z = pk.x; w.w = pk.y; } }
;                 *(u32x4*)rowp = w;
;             }
	v_pk_mul_f32 v[38:39], v[38:39], v[54:55] op_sel_hi:[1,0]
	v_pk_mul_f32 v[36:37], v[36:37], v[54:55] op_sel_hi:[1,0]
	v_pk_mul_f32 v[34:35], v[34:35], v[54:55] op_sel_hi:[1,0]
	v_pk_mul_f32 v[32:33], v[32:33], v[54:55] op_sel_hi:[1,0]
	v_exp_f32_e32 v36, v36
	v_exp_f32_e32 v37, v37
	v_exp_f32_e32 v38, v38
	v_exp_f32_e32 v39, v39
	v_exp_f32_e32 v32, v32
	v_exp_f32_e32 v34, v34
	v_exp_f32_e32 v35, v35
	v_exp_f32_e32 v33, v33
	v_pk_add_f32 v[38:39], v[38:39], 1.0 op_sel_hi:[1,0]
	v_pk_add_f32 v[36:37], v[36:37], 1.0 op_sel_hi:[1,0]
	v_pk_add_f32 v[34:35], v[34:35], 1.0 op_sel_hi:[1,0]
	v_pk_add_f32 v[32:33], v[32:33], 1.0 op_sel_hi:[1,0]
	v_rcp_f32_e32 v36, v36
	v_rcp_f32_e32 v37, v37
	v_rcp_f32_e32 v38, v38
	v_rcp_f32_e32 v39, v39
	v_rcp_f32_e32 v32, v32
	v_rcp_f32_e32 v33, v33
	v_rcp_f32_e32 v34, v34
	v_rcp_f32_e32 v35, v35
	v_mul_f32_e32 v56, v49, v49
	v_pk_mul_f32 v[36:37], v[56:57], v[36:37] op_sel_hi:[0,1]
	v_pk_mul_f32 v[38:39], v[56:57], v[38:39] op_sel_hi:[0,1]
	v_pk_mul_f32 v[32:33], v[56:57], v[32:33] op_sel_hi:[0,1]
	v_pk_mul_f32 v[34:35], v[56:57], v[34:35] op_sel_hi:[0,1]
	v_pk_mul_f32 v[38:39], v[46:47], v[38:39]
	v_pk_mul_f32 v[36:37], v[44:45], v[36:37]
	v_pk_mul_f32 v[42:43], v[42:43], v[34:35]
	v_pk_mul_f32 v[34:35], v[40:41], v[32:33]
	v_cvt_pk_bf16_f32 v32, v36, v37
	v_cvt_pk_bf16_f32 v33, v38, v39
	v_cvt_pk_bf16_f32 v34, v34, v35
	v_cvt_pk_bf16_f32 v35, v42, v43
	v_lshl_add_u64 v[52:53], v[136:137], 0, v[52:53]
	global_store_dwordx4 v[50:51], v[32:35], off
	s_nop 1
	v_add_u32_e32 v32, 0xb0, v156
	v_ashrrev_i32_e32 v33, 31, v32
	v_lshlrev_b64 v[36:37], 6, v[32:33]
	v_mad_i64_i32 v[34:35], s[38:39], v48, s94, v[142:143]
	v_mov_b32_e32 v33, v230
	v_lshl_add_u64 v[34:35], v[34:35], 0, s[28:29]
	v_lshl_add_u64 v[34:35], v[34:35], 0, s[4:5]
	v_lshl_add_u64 v[34:35], v[34:35], 0, v[144:145]
	v_mul_f32_e32 v38, 0xbfb8aa3b, v33
	v_pk_mul_f32 v[22:23], v[22:23], v[38:39] op_sel_hi:[1,0]
	v_pk_mul_f32 v[20:21], v[20:21], v[38:39] op_sel_hi:[1,0]
	v_pk_mul_f32 v[18:19], v[18:19], v[38:39] op_sel_hi:[1,0]
	v_pk_mul_f32 v[16:17], v[16:17], v[38:39] op_sel_hi:[1,0]
	v_exp_f32_e32 v20, v20
	v_exp_f32_e32 v21, v21
	v_exp_f32_e32 v22, v22
	v_exp_f32_e32 v23, v23
	v_exp_f32_e32 v16, v16
	v_exp_f32_e32 v18, v18
	v_exp_f32_e32 v19, v19
	v_exp_f32_e32 v17, v17
	v_pk_add_f32 v[22:23], v[22:23], 1.0 op_sel_hi:[1,0]
	v_pk_add_f32 v[20:21], v[20:21], 1.0 op_sel_hi:[1,0]
	v_pk_add_f32 v[18:19], v[18:19], 1.0 op_sel_hi:[1,0]
	v_pk_add_f32 v[16:17], v[16:17], 1.0 op_sel_hi:[1,0]
	v_rcp_f32_e32 v20, v20
	v_rcp_f32_e32 v21, v21
	v_rcp_f32_e32 v22, v22
	v_rcp_f32_e32 v23, v23
	v_rcp_f32_e32 v16, v16
	v_rcp_f32_e32 v17, v17
	v_rcp_f32_e32 v18, v18
	v_rcp_f32_e32 v19, v19
	v_mul_f32_e32 v40, v33, v33
	v_pk_mul_f32 v[20:21], v[40:41], v[20:21] op_sel_hi:[0,1]
	v_pk_mul_f32 v[22:23], v[40:41], v[22:23] op_sel_hi:[0,1]
	v_pk_mul_f32 v[16:17], v[40:41], v[16:17] op_sel_hi:[0,1]
	v_pk_mul_f32 v[18:19], v[40:41], v[18:19] op_sel_hi:[0,1]
	v_pk_mul_f32 v[22:23], v[30:31], v[22:23]
	v_pk_mul_f32 v[20:21], v[28:29], v[20:21]
	v_pk_mul_f32 v[26:27], v[26:27], v[18:19]
	v_pk_mul_f32 v[18:19], v[24:25], v[16:17]
	v_cvt_pk_bf16_f32 v16, v20, v21
	v_cvt_pk_bf16_f32 v17, v22, v23
	v_cvt_pk_bf16_f32 v18, v18, v19
	v_cvt_pk_bf16_f32 v19, v26, v27
	v_lshl_add_u64 v[36:37], v[136:137], 0, v[36:37]
	global_store_dwordx4 v[34:35], v[16:19], off
	s_nop 1
	v_mad_i64_i32 v[16:17], s[36:37], v32, s94, v[142:143]
	v_lshl_add_u64 v[16:17], v[16:17], 0, s[28:29]
	v_lshl_add_u64 v[16:17], v[16:17], 0, s[4:5]
	v_mov_b32_e32 v19, v231
	v_lshl_add_u64 v[16:17], v[16:17], 0, v[144:145]
	s_mov_b64 s[28:29], -1
	v_mul_f32_e32 v18, 0xbfb8aa3b, v19
	v_pk_mul_f32 v[6:7], v[6:7], v[18:19] op_sel_hi:[1,0]
	v_pk_mul_f32 v[4:5], v[4:5], v[18:19] op_sel_hi:[1,0]
	v_pk_mul_f32 v[2:3], v[2:3], v[18:19] op_sel_hi:[1,0]
	v_pk_mul_f32 v[0:1], v[0:1], v[18:19] op_sel_hi:[1,0]
	v_exp_f32_e32 v4, v4
	v_exp_f32_e32 v5, v5
	v_exp_f32_e32 v6, v6
	v_exp_f32_e32 v7, v7
	v_exp_f32_e32 v0, v0
	v_exp_f32_e32 v2, v2
	v_exp_f32_e32 v3, v3
	v_exp_f32_e32 v1, v1
	v_pk_add_f32 v[6:7], v[6:7], 1.0 op_sel_hi:[1,0]
	v_pk_add_f32 v[4:5], v[4:5], 1.0 op_sel_hi:[1,0]
	v_pk_add_f32 v[2:3], v[2:3], 1.0 op_sel_hi:[1,0]
	v_pk_add_f32 v[0:1], v[0:1], 1.0 op_sel_hi:[1,0]
	v_rcp_f32_e32 v4, v4
	v_rcp_f32_e32 v5, v5
	v_rcp_f32_e32 v6, v6
	v_rcp_f32_e32 v7, v7
	v_rcp_f32_e32 v0, v0
	v_rcp_f32_e32 v1, v1
	v_rcp_f32_e32 v2, v2
	v_rcp_f32_e32 v3, v3
	v_mul_f32_e32 v20, v19, v19
	v_pk_mul_f32 v[4:5], v[20:21], v[4:5] op_sel_hi:[0,1]
	v_pk_mul_f32 v[6:7], v[20:21], v[6:7] op_sel_hi:[0,1]
	v_pk_mul_f32 v[0:1], v[20:21], v[0:1] op_sel_hi:[0,1]
	v_pk_mul_f32 v[2:3], v[20:21], v[2:3] op_sel_hi:[0,1]
	v_pk_mul_f32 v[6:7], v[14:15], v[6:7]
	v_pk_mul_f32 v[4:5], v[12:13], v[4:5]
	v_pk_mul_f32 v[10:11], v[10:11], v[2:3]
	v_pk_mul_f32 v[2:3], v[8:9], v[0:1]
	v_cvt_pk_bf16_f32 v0, v4, v5
	v_cvt_pk_bf16_f32 v1, v6, v7
	v_cvt_pk_bf16_f32 v2, v2, v3
	v_cvt_pk_bf16_f32 v3, v10, v11
	global_store_dwordx4 v[16:17], v[0:3], off
	s_cbranch_vccnz .LBB0_178
	s_andn2_b64 vcc, exec, s[8:9]
	s_cbranch_vccnz .LBB0_177
	s_barrier
	s_branch .LBB0_177

; __device__ __forceinline__ float rstd_row4(const float* ssrow, int fq) { const f32x4 a = *(const f32x4*)(ssrow + 4 * fq); float ss = (a[0] + a[1]) + (a[2] + a[3]);
;     ss += __shfl_xor(ss, 16); ss += __shfl_xor(ss, 32); return __builtin_amdgcn_rsqf(ss * (1.0f / 1024.0f) + 1e-6f); }
;     __device__ __forceinline__ void operator()(const f32x4 (&acc)[2][2][4][2], const Unit& u, int wr, int wc, int fr, int fq) const {
; #pragma unroll
;         for (int ai = 0; ai < 2; ++ai)
; #pragma unroll
;             for (int m = 0; m < 4; ++m) {
;                 const int row = u.pm * BM + ai * HALF + wr * 64 + m * 16 + fr; const float rs = rstd_row4(ss + (size_t)row * 16, fq);
;                 bf16_t* rowp = out + (size_t)row * 2816 + u.pn * 128 + wc * 32 + fq * 8;
;                 u32x4 w;
;                 const float rsl = rs * (-1.4426950408889634f), rs2 = rs * rs;
; #pragma unroll
;                 for (int n = 0; n < 2; ++n) {
;                     const f32x4 ta = acc[ai][0][m][n] * rsl, gu = acc[ai][0][m][n] * acc[ai][1][m][n]; f32x4 t;
.LBB0_714:
	s_lshl_b32 s9, s16, 8
	v_add_u32_e32 v156, s9, v158
	v_ashrrev_i32_e32 v157, 31, v156
	v_lshlrev_b64 v[142:143], 6, v[156:157]
	v_lshl_add_u64 v[142:143], v[136:137], 0, v[142:143]
	global_load_dwordx4 v[164:167], v[142:143], off
	global_load_dwordx4 v[176:179], v[142:143], off offset:1024
	global_load_dwordx4 v[180:183], v[142:143], off offset:2048
	global_load_dwordx4 v[184:187], v[142:143], off offset:3072
	v_lshl_add_u64 v[216:217], v[150:151], 4, v[142:143]
	global_load_dwordx4 v[188:191], v[216:217], off
	global_load_dwordx4 v[192:195], v[216:217], off offset:1024
	global_load_dwordx4 v[196:199], v[216:217], off offset:2048
	global_load_dwordx4 v[220:223], v[216:217], off offset:3072
	v_and_b32_e32 v170, 64, v203
	v_xor_b32_e32 v157, 16, v203
	v_pk_mul_f32 v[168:169], v[112:113], v[120:121]
	v_add_u32_e32 v120, 64, v170
	v_cmp_lt_i32_e32 vcc, v157, v120
	v_xor_b32_e32 v171, 32, v203
	v_pk_mul_f32 v[126:127], v[118:119], v[126:127]
	v_cndmask_b32_e32 v121, v203, v157, vcc
	v_lshlrev_b32_e32 v121, 2, v121
	v_cmp_lt_i32_e32 vcc, v171, v120
	v_pk_mul_f32 v[124:125], v[116:117], v[124:125]
	v_pk_mul_f32 v[122:123], v[114:115], v[122:123]
	v_cndmask_b32_e32 v120, v203, v171, vcc
	v_lshlrev_b32_e32 v120, 2, v120
	s_lshl_b32 s16, s17, 7
	v_mov_b64_e32 v[142:143], s[80:81]
	s_ashr_i32 s17, s16, 31
	s_lshl_b64 s[16:17], s[16:17], 1
	v_add_u32_e32 v170, s9, v160
	v_ashrrev_i32_e32 v171, 31, v170
	v_pk_mul_f32 v[110:111], v[102:103], v[110:111]
	v_pk_mul_f32 v[108:109], v[100:101], v[108:109]
	v_pk_mul_f32 v[106:107], v[98:99], v[106:107]
	v_pk_mul_f32 v[104:105], v[96:97], v[104:105]
	v_pk_mul_f32 v[94:95], v[86:87], v[94:95]
	v_pk_mul_f32 v[92:93], v[84:85], v[92:93]
	v_pk_mul_f32 v[90:91], v[82:83], v[90:91]
	v_pk_mul_f32 v[88:89], v[80:81], v[88:89]
	v_pk_mul_f32 v[78:79], v[70:71], v[78:79]
	v_pk_mul_f32 v[76:77], v[68:69], v[76:77]
	v_pk_mul_f32 v[74:75], v[66:67], v[74:75]
	v_pk_mul_f32 v[72:73], v[64:65], v[72:73]
	v_pk_mul_f32 v[62:63], v[54:55], v[62:63]
	v_pk_mul_f32 v[60:61], v[52:53], v[60:61]
	v_pk_mul_f32 v[58:59], v[50:51], v[58:59]
	v_pk_mul_f32 v[56:57], v[48:49], v[56:57]
	v_pk_mul_f32 v[46:47], v[38:39], v[46:47]
	v_pk_mul_f32 v[44:45], v[36:37], v[44:45]
	v_pk_mul_f32 v[42:43], v[34:35], v[42:43]
	v_pk_mul_f32 v[40:41], v[32:33], v[40:41]
	v_pk_mul_f32 v[30:31], v[22:23], v[30:31]
	v_pk_mul_f32 v[28:29], v[20:21], v[28:29]
	v_pk_mul_f32 v[26:27], v[18:19], v[26:27]
	v_pk_mul_f32 v[24:25], v[16:17], v[24:25]
	v_pk_mul_f32 v[14:15], v[6:7], v[14:15]
	v_pk_mul_f32 v[12:13], v[4:5], v[12:13]
	v_pk_mul_f32 v[10:11], v[2:3], v[10:11]
	v_pk_mul_f32 v[8:9], v[0:1], v[8:9]
	s_andn2_b64 vcc, exec, s[36:37]
	s_waitcnt vmcnt(0)
	v_add_f32_e32 v232, v164, v165
	v_add_f32_e32 v233, v166, v167
	v_add_f32_e32 v224, v232, v233
	v_add_f32_e32 v232, v176, v177
	v_add_f32_e32 v233, v178, v179
	v_add_f32_e32 v225, v232, v233
	v_add_f32_e32 v232, v180, v181
	v_add_f32_e32 v233, v182, v183
	v_add_f32_e32 v226, v232, v233
	v_add_f32_e32 v232, v184, v185
	v_add_f32_e32 v233, v186, v187
	v_add_f32_e32 v227, v232, v233
	v_add_f32_e32 v232, v188, v189
	v_add_f32_e32 v233, v190, v191
	v_add_f32_e32 v228, v232, v233
	v_add_f32_e32 v232, v192, v193
	v_add_f32_e32 v233, v194, v195
	v_add_f32_e32 v229, v232, v233
	v_add_f32_e32 v232, v196, v197
	v_add_f32_e32 v233, v198, v199
	v_add_f32_e32 v230, v232, v233
	v_add_f32_e32 v232, v220, v221
	v_add_f32_e32 v233, v222, v223
	v_add_f32_e32 v231, v232, v233
	ds_bpermute_b32 v240, v121, v224
	ds_bpermute_b32 v241, v121, v225
	ds_bpermute_b32 v242, v121, v226
	ds_bpermute_b32 v243, v121, v227
	ds_bpermute_b32 v244, v121, v228
	ds_bpermute_b32 v245, v121, v229
	ds_bpermute_b32 v246, v121, v230
	ds_bpermute_b32 v247, v121, v231
	s_waitcnt lgkmcnt(0)
	v_add_f32_e32 v224, v224, v240
	v_add_f32_e32 v225, v225, v241
	v_add_f32_e32 v226, v226, v242
	v_add_f32_e32 v227, v227, v243
	v_add_f32_e32 v228, v228, v244
	v_add_f32_e32 v229, v229, v245
	v_add_f32_e32 v230, v230, v246
	v_add_f32_e32 v231, v231, v247
	ds_bpermute_b32 v240, v120, v224
	ds_bpermute_b32 v241, v120, v225
	ds_bpermute_b32 v242, v120, v226
	ds_bpermute_b32 v243, v120, v227
	ds_bpermute_b32 v244, v120, v228
	ds_bpermute_b32 v245, v120, v229
	ds_bpermute_b32 v246, v120, v230
	ds_bpermute_b32 v247, v120, v231
	s_waitcnt lgkmcnt(0)
; __device__ __forceinline__ u32x2 pack4(f32x4 v) { u32x2 w; w.x = cvt_pk_bf16(v[0], v[1]); w.y = cvt_pk_bf16(v[2], v[3]); return w; }
; __device__ __forceinline__ float rstd_row4(const float* ssrow, int fq) { const f32x4 a = *(const f32x4*)(ssrow + 4 * fq); float ss = (a[0] + a[1]) + (a[2] + a[3]);
;     ss += __shfl_xor(ss, 16); ss += __shfl_xor(ss, 32); return __builtin_amdgcn_rsqf(ss * (1.0f / 1024.0f) + 1e-6f); }
;     __device__ __forceinline__ void operator()(const f32x4 (&acc)[2][2][4][2], const Unit& u, int wr, int wc, int fr, int fq) const {
;     ...
;             for (int m = 0; m < 4; ++m) {
;                 const int row = u.pm * BM + ai * HALF + wr * 64 + m * 16 + fr; const float rs = rstd_row4(ss + (size_t)row * 16, fq);
;                 bf16_t* rowp = out + (size_t)row * 2816 + u.pn * 128 + wc * 32 + fq * 8;
;                 u32x4 w;
;                 const float rsl = rs * (-1.4426950408889634f), rs2 = rs * rs;
; #pragma unroll
;                 for (int n = 0; n < 2; ++n) {
;                     const f32x4 ta = acc[ai][0][m][n] * rsl, gu = acc[ai][0][m][n] * acc[ai][1][m][n]; f32x4 t;
;                     t[0] = __builtin_amdgcn_exp2f(ta[0]); t[1] = __builtin_amdgcn_exp2f(ta[1]); t[2] = __builtin_amdgcn_exp2f(ta[2]); t[3] = __builtin_amdgcn_exp2f(ta[3]);
;                     const f32x4 dn = t + 1.0f; f32x4 r;
;                     r[0] = __builtin_amdgcn_rcpf(dn[0]); r[1] = __builtin_amdgcn_rcpf(dn[1]); r[2] = __builtin_amdgcn_rcpf(dn[2]); r[3] = __builtin_amdgcn_rcpf(dn[3]);
;                     const f32x4 h = gu * (r * rs2);
;                     const u32x2 pk = pack4(h); if (n == 0) { w.x = pk.x; w.y = pk.y; } else { w.z = pk.x; w.w = pk.y; } }
	v_add_f32_e32 v224, v224, v240
	v_add_f32_e32 v225, v225, v241
	v_add_f32_e32 v226, v226, v242
	v_add_f32_e32 v227, v227, v243
	v_add_f32_e32 v228, v228, v244
	v_add_f32_e32 v229, v229, v245
	v_add_f32_e32 v230, v230, v246
	v_add_f32_e32 v231, v231, v247
	v_fmamk_f32 v224, v224, 0x3a800000, v201
	v_fmamk_f32 v225, v225, 0x3a800000, v201
	v_fmamk_f32 v226, v226, 0x3a800000, v201
	v_fmamk_f32 v227, v227, 0x3a800000, v201
	v_fmamk_f32 v228, v228, 0x3a800000, v201
	v_fmamk_f32 v229, v229, 0x3a800000, v201
	v_fmamk_f32 v230, v230, 0x3a800000, v201
	v_fmamk_f32 v231, v231, 0x3a800000, v201
	v_rsq_f32_e32 v224, v224
	v_rsq_f32_e32 v225, v225
	v_rsq_f32_e32 v226, v226
	v_rsq_f32_e32 v227, v227
	v_rsq_f32_e32 v228, v228
	v_rsq_f32_e32 v229, v229
	v_rsq_f32_e32 v230, v230
	v_rsq_f32_e32 v231, v231
	v_mad_i64_i32 v[164:165], s[18:19], v156, s94, v[142:143]
	v_lshl_add_u64 v[164:165], v[164:165], 0, s[16:17]
	v_lshl_add_u64 v[164:165], v[164:165], 0, s[4:5]
	v_lshlrev_b64 v[166:167], 6, v[170:171]
	v_lshl_add_u64 v[164:165], v[164:165], 0, v[144:145]
	v_lshl_add_u64 v[166:167], v[136:137], 0, v[166:167]
	v_mov_b32_e32 v157, v224
	s_nop 0
	v_mul_f32_e32 v172, 0xbfb8aa3b, v157
	v_pk_mul_f32 v[118:119], v[118:119], v[172:173] op_sel_hi:[1,0]
	v_pk_mul_f32 v[116:117], v[116:117], v[172:173] op_sel_hi:[1,0]
	v_pk_mul_f32 v[114:115], v[114:115], v[172:173] op_sel_hi:[1,0]
	v_pk_mul_f32 v[112:113], v[112:113], v[172:173] op_sel_hi:[1,0]
	v_exp_f32_e32 v116, v116
	v_exp_f32_e32 v117, v117
	v_exp_f32_e32 v118, v118
	v_exp_f32_e32 v119, v119
	v_exp_f32_e32 v112, v112
	v_exp_f32_e32 v114, v114
	v_exp_f32_e32 v115, v115
	v_exp_f32_e32 v113, v113
	v_pk_add_f32 v[118:119], v[118:119], 1.0 op_sel_hi:[1,0]
	v_pk_add_f32 v[116:117], v[116:117], 1.0 op_sel_hi:[1,0]
	v_pk_add_f32 v[114:115], v[114:115], 1.0 op_sel_hi:[1,0]
	v_pk_add_f32 v[112:113], v[112:113], 1.0 op_sel_hi:[1,0]
	v_rcp_f32_e32 v116, v116
	v_rcp_f32_e32 v117, v117
	v_rcp_f32_e32 v118, v118
	v_rcp_f32_e32 v119, v119
	v_rcp_f32_e32 v112, v112
	v_rcp_f32_e32 v113, v113
	v_rcp_f32_e32 v114, v114
	v_rcp_f32_e32 v115, v115
	v_mul_f32_e32 v174, v157, v157
	v_pk_mul_f32 v[116:117], v[174:175], v[116:117] op_sel_hi:[0,1]
	v_pk_mul_f32 v[118:119], v[174:175], v[118:119] op_sel_hi:[0,1]
	v_pk_mul_f32 v[112:113], v[174:175], v[112:113] op_sel_hi:[0,1]
	v_pk_mul_f32 v[114:115], v[174:175], v[114:115] op_sel_hi:[0,1]
	v_pk_mul_f32 v[118:119], v[126:127], v[118:119]
	v_pk_mul_f32 v[116:117], v[124:125], v[116:117]
	v_pk_mul_f32 v[122:123], v[122:123], v[114:115]
	v_pk_mul_f32 v[114:115], v[168:169], v[112:113]
	v_cvt_pk_bf16_f32 v112, v116, v117
	v_cvt_pk_bf16_f32 v113, v118, v119
	v_cvt_pk_bf16_f32 v114, v114, v115
	v_cvt_pk_bf16_f32 v115, v122, v123
	global_store_dwordx4 v[164:165], v[112:115], off
	s_nop 1
	v_add_u32_e32 v112, s9, v161
	v_ashrrev_i32_e32 v113, 31, v112
	v_lshlrev_b64 v[116:117], 6, v[112:113]
	v_mad_i64_i32 v[114:115], s[18:19], v170, s94, v[142:143]
	v_mov_b32_e32 v113, v225
	v_lshl_add_u64 v[114:115], v[114:115], 0, s[16:17]
	v_lshl_add_u64 v[114:115], v[114:115], 0, s[4:5]
	v_lshl_add_u64 v[114:115], v[114:115], 0, v[144:145]
	v_mul_f32_e32 v118, 0xbfb8aa3b, v113
	v_pk_mul_f32 v[102:103], v[102:103], v[118:119] op_sel_hi:[1,0]
	v_pk_mul_f32 v[100:101], v[100:101], v[118:119] op_sel_hi:[1,0]
	v_pk_mul_f32 v[98:99], v[98:99], v[118:119] op_sel_hi:[1,0]
	v_pk_mul_f32 v[96:97], v[96:97], v[118:119] op_sel_hi:[1,0]
	v_exp_f32_e32 v100, v100
	v_exp_f32_e32 v101, v101
	v_exp_f32_e32 v102, v102
	v_exp_f32_e32 v103, v103
	v_exp_f32_e32 v96, v96
	v_exp_f32_e32 v98, v98
	v_exp_f32_e32 v99, v99
	v_exp_f32_e32 v97, v97
	v_pk_add_f32 v[102:103], v[102:103], 1.0 op_sel_hi:[1,0]
	v_pk_add_f32 v[100:101], v[100:101], 1.0 op_sel_hi:[1,0]
	v_pk_add_f32 v[98:99], v[98:99], 1.0 op_sel_hi:[1,0]
	v_pk_add_f32 v[96:97], v[96:97], 1.0 op_sel_hi:[1,0]
	v_rcp_f32_e32 v100, v100
	v_rcp_f32_e32 v101, v101
	v_rcp_f32_e32 v102, v102
	v_rcp_f32_e32 v103, v103
	v_rcp_f32_e32 v96, v96
	v_rcp_f32_e32 v97, v97
	v_rcp_f32_e32 v98, v98
	v_rcp_f32_e32 v99, v99
	v_mul_f32_e32 v122, v113, v113
	v_pk_mul_f32 v[100:101], v[122:123], v[100:101] op_sel_hi:[0,1]
	v_pk_mul_f32 v[102:103], v[122:123], v[102:103] op_sel_hi:[0,1]
	v_pk_mul_f32 v[96:97], v[122:123], v[96:97] op_sel_hi:[0,1]
	v_pk_mul_f32 v[98:99], v[122:123], v[98:99] op_sel_hi:[0,1]
	v_pk_mul_f32 v[102:103], v[110:111], v[102:103]
	v_pk_mul_f32 v[100:101], v[108:109], v[100:101]
	v_pk_mul_f32 v[106:107], v[106:107], v[98:99]
	v_pk_mul_f32 v[98:99], v[104:105], v[96:97]
	v_cvt_pk_bf16_f32 v96, v100, v101
	v_cvt_pk_bf16_f32 v97, v102, v103
	v_cvt_pk_bf16_f32 v98, v98, v99
	v_cvt_pk_bf16_f32 v99, v106, v107
	v_lshl_add_u64 v[116:117], v[136:137], 0, v[116:117]
	global_store_dwordx4 v[114:115], v[96:99], off
	s_nop 1
	v_add_u32_e32 v96, s9, v162
	v_ashrrev_i32_e32 v97, 31, v96
	v_lshlrev_b64 v[100:101], 6, v[96:97]
	v_mad_i64_i32 v[98:99], s[18:19], v112, s94, v[142:143]
	v_mov_b32_e32 v97, v226
	v_lshl_add_u64 v[98:99], v[98:99], 0, s[16:17]
	v_lshl_add_u64 v[98:99], v[98:99], 0, s[4:5]
	v_lshl_add_u64 v[98:99], v[98:99], 0, v[144:145]
	v_mul_f32_e32 v102, 0xbfb8aa3b, v97
	v_pk_mul_f32 v[86:87], v[86:87], v[102:103] op_sel_hi:[1,0]
	v_pk_mul_f32 v[84:85], v[84:85], v[102:103] op_sel_hi:[1,0]
	v_pk_mul_f32 v[82:83], v[82:83], v[102:103] op_sel_hi:[1,0]
	v_pk_mul_f32 v[80:81], v[80:81], v[102:103] op_sel_hi:[1,0]
	v_exp_f32_e32 v84, v84
	v_exp_f32_e32 v85, v85
	v_exp_f32_e32 v86, v86
	v_exp_f32_e32 v87, v87
	v_exp_f32_e32 v80, v80
	v_exp_f32_e32 v82, v82
	v_exp_f32_e32 v83, v83
	v_exp_f32_e32 v81, v81
	v_pk_add_f32 v[86:87], v[86:87], 1.0 op_sel_hi:[1,0]
; __device__ __forceinline__ u32x2 pack4(f32x4 v) { u32x2 w; w.x = cvt_pk_bf16(v[0], v[1]); w.y = cvt_pk_bf16(v[2], v[3]); return w; }
;     __device__ __forceinline__ void operator()(const f32x4 (&acc)[2][2][4][2], const Unit& u, int wr, int wc, int fr, int fq) const {
;     ...
;             for (int m = 0; m < 4; ++m) {
;                 const int row = u.pm * BM + ai * HALF + wr * 64 + m * 16 + fr; const float rs = rstd_row4(ss + (size_t)row * 16, fq);
;                 bf16_t* rowp = out + (size_t)row * 2816 + u.pn * 128 + wc * 32 + fq * 8;
;                 u32x4 w;
;                 const float rsl = rs * (-1.4426950408889634f), rs2 = rs * rs;
; #pragma unroll
;                 for (int n = 0; n < 2; ++n) {
;                     const f32x4 ta = acc[ai][0][m][n] * rsl, gu = acc[ai][0][m][n] * acc[ai][1][m][n]; f32x4 t;
;                     t[0] = __builtin_amdgcn_exp2f(ta[0]); t[1] = __builtin_amdgcn_exp2f(ta[1]); t[2] = __builtin_amdgcn_exp2f(ta[2]); t[3] = __builtin_amdgcn_exp2f(ta[3]);
;                     const f32x4 dn = t + 1.0f; f32x4 r;
;                     r[0] = __builtin_amdgcn_rcpf(dn[0]); r[1] = __builtin_amdgcn_rcpf(dn[1]); r[2] = __builtin_amdgcn_rcpf(dn[2]); r[3] = __builtin_amdgcn_rcpf(dn[3]);
;                     const f32x4 h = gu * (r * rs2);
;                     const u32x2 pk = pack4(h); if (n == 0) { w.x = pk.x; w.y = pk.y; } else { w.z = pk.x; w.w = pk.y; } }
;                 *(u32x4*)rowp = w;
	v_pk_add_f32 v[84:85], v[84:85], 1.0 op_sel_hi:[1,0]
	v_pk_add_f32 v[82:83], v[82:83], 1.0 op_sel_hi:[1,0]
	v_pk_add_f32 v[80:81], v[80:81], 1.0 op_sel_hi:[1,0]
	v_rcp_f32_e32 v84, v84
	v_rcp_f32_e32 v85, v85
	v_rcp_f32_e32 v86, v86
	v_rcp_f32_e32 v87, v87
	v_rcp_f32_e32 v80, v80
	v_rcp_f32_e32 v81, v81
	v_rcp_f32_e32 v82, v82
	v_rcp_f32_e32 v83, v83
	v_mul_f32_e32 v104, v97, v97
	v_pk_mul_f32 v[84:85], v[104:105], v[84:85] op_sel_hi:[0,1]
	v_pk_mul_f32 v[86:87], v[104:105], v[86:87] op_sel_hi:[0,1]
	v_pk_mul_f32 v[80:81], v[104:105], v[80:81] op_sel_hi:[0,1]
	v_pk_mul_f32 v[82:83], v[104:105], v[82:83] op_sel_hi:[0,1]
	v_pk_mul_f32 v[86:87], v[94:95], v[86:87]
	v_pk_mul_f32 v[84:85], v[92:93], v[84:85]
	v_pk_mul_f32 v[90:91], v[90:91], v[82:83]
	v_pk_mul_f32 v[82:83], v[88:89], v[80:81]
	v_cvt_pk_bf16_f32 v80, v84, v85
	v_cvt_pk_bf16_f32 v81, v86, v87
	v_cvt_pk_bf16_f32 v82, v82, v83
	v_cvt_pk_bf16_f32 v83, v90, v91
	v_lshl_add_u64 v[100:101], v[136:137], 0, v[100:101]
	global_store_dwordx4 v[98:99], v[80:83], off
	s_nop 1
	v_mad_i64_i32 v[80:81], s[18:19], v96, s94, v[142:143]
	v_lshl_add_u64 v[80:81], v[80:81], 0, s[16:17]
	v_lshl_add_u64 v[80:81], v[80:81], 0, s[4:5]
	v_add_u32_e32 v82, 0x80, v156
	v_ashrrev_i32_e32 v83, 31, v82
	v_lshl_add_u64 v[80:81], v[80:81], 0, v[144:145]
	v_mov_b32_e32 v87, v227
	v_lshlrev_b64 v[84:85], 6, v[82:83]
	v_lshl_add_u64 v[84:85], v[136:137], 0, v[84:85]
	v_mul_f32_e32 v86, 0xbfb8aa3b, v87
	v_pk_mul_f32 v[70:71], v[70:71], v[86:87] op_sel_hi:[1,0]
	v_pk_mul_f32 v[68:69], v[68:69], v[86:87] op_sel_hi:[1,0]
	v_pk_mul_f32 v[66:67], v[66:67], v[86:87] op_sel_hi:[1,0]
	v_pk_mul_f32 v[64:65], v[64:65], v[86:87] op_sel_hi:[1,0]
	v_exp_f32_e32 v68, v68
	v_exp_f32_e32 v69, v69
	v_exp_f32_e32 v70, v70
	v_exp_f32_e32 v71, v71
	v_exp_f32_e32 v64, v64
	v_exp_f32_e32 v66, v66
	v_exp_f32_e32 v67, v67
	v_exp_f32_e32 v65, v65
	v_pk_add_f32 v[70:71], v[70:71], 1.0 op_sel_hi:[1,0]
	v_pk_add_f32 v[68:69], v[68:69], 1.0 op_sel_hi:[1,0]
	v_pk_add_f32 v[66:67], v[66:67], 1.0 op_sel_hi:[1,0]
	v_pk_add_f32 v[64:65], v[64:65], 1.0 op_sel_hi:[1,0]
	v_rcp_f32_e32 v68, v68
	v_rcp_f32_e32 v69, v69
	v_rcp_f32_e32 v70, v70
	v_rcp_f32_e32 v71, v71
	v_rcp_f32_e32 v64, v64
	v_rcp_f32_e32 v65, v65
	v_rcp_f32_e32 v66, v66
	v_rcp_f32_e32 v67, v67
	v_mul_f32_e32 v88, v87, v87
	v_pk_mul_f32 v[68:69], v[88:89], v[68:69] op_sel_hi:[0,1]
	v_pk_mul_f32 v[70:71], v[88:89], v[70:71] op_sel_hi:[0,1]
	v_pk_mul_f32 v[64:65], v[88:89], v[64:65] op_sel_hi:[0,1]
	v_pk_mul_f32 v[66:67], v[88:89], v[66:67] op_sel_hi:[0,1]
	v_pk_mul_f32 v[70:71], v[78:79], v[70:71]
	v_pk_mul_f32 v[68:69], v[76:77], v[68:69]
	v_pk_mul_f32 v[74:75], v[74:75], v[66:67]
	v_pk_mul_f32 v[66:67], v[72:73], v[64:65]
	v_cvt_pk_bf16_f32 v64, v68, v69
	v_cvt_pk_bf16_f32 v65, v70, v71
	v_cvt_pk_bf16_f32 v66, v66, v67
	v_cvt_pk_bf16_f32 v67, v74, v75
	global_store_dwordx4 v[80:81], v[64:67], off
	s_nop 1
	v_add_u32_e32 v64, 0x90, v156
	v_ashrrev_i32_e32 v65, 31, v64
	v_lshlrev_b64 v[68:69], 6, v[64:65]
	v_mad_i64_i32 v[66:67], s[18:19], v82, s94, v[142:143]
	v_mov_b32_e32 v65, v228
	v_lshl_add_u64 v[66:67], v[66:67], 0, s[16:17]
	v_lshl_add_u64 v[66:67], v[66:67], 0, s[4:5]
	v_lshl_add_u64 v[66:67], v[66:67], 0, v[144:145]
	v_mul_f32_e32 v70, 0xbfb8aa3b, v65
	v_pk_mul_f32 v[54:55], v[54:55], v[70:71] op_sel_hi:[1,0]
	v_pk_mul_f32 v[52:53], v[52:53], v[70:71] op_sel_hi:[1,0]
	v_pk_mul_f32 v[50:51], v[50:51], v[70:71] op_sel_hi:[1,0]
	v_pk_mul_f32 v[48:49], v[48:49], v[70:71] op_sel_hi:[1,0]
	v_exp_f32_e32 v52, v52
	v_exp_f32_e32 v53, v53
	v_exp_f32_e32 v54, v54
	v_exp_f32_e32 v55, v55
	v_exp_f32_e32 v48, v48
	v_exp_f32_e32 v50, v50
	v_exp_f32_e32 v51, v51
	v_exp_f32_e32 v49, v49
	v_pk_add_f32 v[54:55], v[54:55], 1.0 op_sel_hi:[1,0]
	v_pk_add_f32 v[52:53], v[52:53], 1.0 op_sel_hi:[1,0]
	v_pk_add_f32 v[50:51], v[50:51], 1.0 op_sel_hi:[1,0]
	v_pk_add_f32 v[48:49], v[48:49], 1.0 op_sel_hi:[1,0]
	v_rcp_f32_e32 v52, v52
	v_rcp_f32_e32 v53, v53
	v_rcp_f32_e32 v54, v54
	v_rcp_f32_e32 v55, v55
	v_rcp_f32_e32 v48, v48
	v_rcp_f32_e32 v49, v49
	v_rcp_f32_e32 v50, v50
	v_rcp_f32_e32 v51, v51
	v_mul_f32_e32 v72, v65, v65
	v_pk_mul_f32 v[52:53], v[72:73], v[52:53] op_sel_hi:[0,1]
	v_pk_mul_f32 v[54:55], v[72:73], v[54:55] op_sel_hi:[0,1]
	v_pk_mul_f32 v[48:49], v[72:73], v[48:49] op_sel_hi:[0,1]
	v_pk_mul_f32 v[50:51], v[72:73], v[50:51] op_sel_hi:[0,1]
	v_pk_mul_f32 v[54:55], v[62:63], v[54:55]
	v_pk_mul_f32 v[52:53], v[60:61], v[52:53]
	v_pk_mul_f32 v[58:59], v[58:59], v[50:51]
	v_pk_mul_f32 v[50:51], v[56:57], v[48:49]
	v_cvt_pk_bf16_f32 v48, v52, v53
	v_cvt_pk_bf16_f32 v49, v54, v55
	v_cvt_pk_bf16_f32 v50, v50, v51
	v_cvt_pk_bf16_f32 v51, v58, v59
	v_lshl_add_u64 v[68:69], v[136:137], 0, v[68:69]
	global_store_dwordx4 v[66:67], v[48:51], off
	s_nop 1
	v_add_u32_e32 v48, 0xa0, v156
	v_ashrrev_i32_e32 v49, 31, v48
	v_lshlrev_b64 v[52:53], 6, v[48:49]
	v_mad_i64_i32 v[50:51], s[18:19], v64, s94, v[142:143]
	v_mov_b32_e32 v49, v229
	v_lshl_add_u64 v[50:51], v[50:51], 0, s[16:17]
	v_lshl_add_u64 v[50:51], v[50:51], 0, s[4:5]
	v_lshl_add_u64 v[50:51], v[50:51], 0, v[144:145]
	v_mul_f32_e32 v54, 0xbfb8aa3b, v49
; __device__ __forceinline__ u32x2 pack4(f32x4 v) { u32x2 w; w.x = cvt_pk_bf16(v[0], v[1]); w.y = cvt_pk_bf16(v[2], v[3]); return w; }
;     __device__ __forceinline__ void operator()(const f32x4 (&acc)[2][2][4][2], const Unit& u, int wr, int wc, int fr, int fq) const {
;     ...
;             for (int m = 0; m < 4; ++m) {
;                 const int row = u.pm * BM + ai * HALF + wr * 64 + m * 16 + fr; const float rs = rstd_row4(ss + (size_t)row * 16, fq);
;                 bf16_t* rowp = out + (size_t)row * 2816 + u.pn * 128 + wc * 32 + fq * 8;
;                 u32x4 w;
;                 const float rsl = rs * (-1.4426950408889634f), rs2 = rs * rs;
; #pragma unroll
;                 for (int n = 0; n < 2; ++n) {
;                     const f32x4 ta = acc[ai][0][m][n] * rsl, gu = acc[ai][0][m][n] * acc[ai][1][m][n]; f32x4 t;
;                     t[0] = __builtin_amdgcn_exp2f(ta[0]); t[1] = __builtin_amdgcn_exp2f(ta[1]); t[2] = __builtin_amdgcn_exp2f(ta[2]); t[3] = __builtin_amdgcn_exp2f(ta[3]);
;                     const f32x4 dn = t + 1.0f; f32x4 r;
;                     r[0] = __builtin_amdgcn_rcpf(dn[0]); r[1] = __builtin_amdgcn_rcpf(dn[1]); r[2] = __builtin_amdgcn_rcpf(dn[2]); r[3] = __builtin_amdgcn_rcpf(dn[3]);
;                     const f32x4 h = gu * (r * rs2);
;                     const u32x2 pk = pack4(h); if (n == 0) { w.x = pk.x; w.y = pk.y; } else { w.z = pk.x; w.w = pk.y; } }
;                 *(u32x4*)rowp = w;
;             }
	v_pk_mul_f32 v[38:39], v[38:39], v[54:55] op_sel_hi:[1,0]
	v_pk_mul_f32 v[36:37], v[36:37], v[54:55] op_sel_hi:[1,0]
	v_pk_mul_f32 v[34:35], v[34:35], v[54:55] op_sel_hi:[1,0]
	v_pk_mul_f32 v[32:33], v[32:33], v[54:55] op_sel_hi:[1,0]
	v_exp_f32_e32 v36, v36
	v_exp_f32_e32 v37, v37
	v_exp_f32_e32 v38, v38
	v_exp_f32_e32 v39, v39
	v_exp_f32_e32 v32, v32
	v_exp_f32_e32 v34, v34
	v_exp_f32_e32 v35, v35
	v_exp_f32_e32 v33, v33
	v_pk_add_f32 v[38:39], v[38:39], 1.0 op_sel_hi:[1,0]
	v_pk_add_f32 v[36:37], v[36:37], 1.0 op_sel_hi:[1,0]
	v_pk_add_f32 v[34:35], v[34:35], 1.0 op_sel_hi:[1,0]
	v_pk_add_f32 v[32:33], v[32:33], 1.0 op_sel_hi:[1,0]
	v_rcp_f32_e32 v36, v36
	v_rcp_f32_e32 v37, v37
	v_rcp_f32_e32 v38, v38
	v_rcp_f32_e32 v39, v39
	v_rcp_f32_e32 v32, v32
	v_rcp_f32_e32 v33, v33
	v_rcp_f32_e32 v34, v34
	v_rcp_f32_e32 v35, v35
	v_mul_f32_e32 v56, v49, v49
	v_pk_mul_f32 v[36:37], v[56:57], v[36:37] op_sel_hi:[0,1]
	v_pk_mul_f32 v[38:39], v[56:57], v[38:39] op_sel_hi:[0,1]
	v_pk_mul_f32 v[32:33], v[56:57], v[32:33] op_sel_hi:[0,1]
	v_pk_mul_f32 v[34:35], v[56:57], v[34:35] op_sel_hi:[0,1]
	v_pk_mul_f32 v[38:39], v[46:47], v[38:39]
	v_pk_mul_f32 v[36:37], v[44:45], v[36:37]
	v_pk_mul_f32 v[42:43], v[42:43], v[34:35]
	v_pk_mul_f32 v[34:35], v[40:41], v[32:33]
	v_cvt_pk_bf16_f32 v32, v36, v37
	v_cvt_pk_bf16_f32 v33, v38, v39
	v_cvt_pk_bf16_f32 v34, v34, v35
	v_cvt_pk_bf16_f32 v35, v42, v43
	v_lshl_add_u64 v[52:53], v[136:137], 0, v[52:53]
	global_store_dwordx4 v[50:51], v[32:35], off
	s_nop 1
	v_add_u32_e32 v32, 0xb0, v156
	v_ashrrev_i32_e32 v33, 31, v32
	v_lshlrev_b64 v[36:37], 6, v[32:33]
	v_mad_i64_i32 v[34:35], s[18:19], v48, s94, v[142:143]
	v_mov_b32_e32 v33, v230
	v_lshl_add_u64 v[34:35], v[34:35], 0, s[16:17]
	v_lshl_add_u64 v[34:35], v[34:35], 0, s[4:5]
	v_lshl_add_u64 v[34:35], v[34:35], 0, v[144:145]
	v_mul_f32_e32 v38, 0xbfb8aa3b, v33
	v_pk_mul_f32 v[22:23], v[22:23], v[38:39] op_sel_hi:[1,0]
	v_pk_mul_f32 v[20:21], v[20:21], v[38:39] op_sel_hi:[1,0]
	v_pk_mul_f32 v[18:19], v[18:19], v[38:39] op_sel_hi:[1,0]
	v_pk_mul_f32 v[16:17], v[16:17], v[38:39] op_sel_hi:[1,0]
	v_exp_f32_e32 v20, v20
	v_exp_f32_e32 v21, v21
	v_exp_f32_e32 v22, v22
	v_exp_f32_e32 v23, v23
	v_exp_f32_e32 v16, v16
	v_exp_f32_e32 v18, v18
	v_exp_f32_e32 v19, v19
	v_exp_f32_e32 v17, v17
	v_pk_add_f32 v[22:23], v[22:23], 1.0 op_sel_hi:[1,0]
	v_pk_add_f32 v[20:21], v[20:21], 1.0 op_sel_hi:[1,0]
	v_pk_add_f32 v[18:19], v[18:19], 1.0 op_sel_hi:[1,0]
	v_pk_add_f32 v[16:17], v[16:17], 1.0 op_sel_hi:[1,0]
	v_rcp_f32_e32 v20, v20
	v_rcp_f32_e32 v21, v21
	v_rcp_f32_e32 v22, v22
	v_rcp_f32_e32 v23, v23
	v_rcp_f32_e32 v16, v16
	v_rcp_f32_e32 v17, v17
	v_rcp_f32_e32 v18, v18
	v_rcp_f32_e32 v19, v19
	v_mul_f32_e32 v40, v33, v33
	v_pk_mul_f32 v[20:21], v[40:41], v[20:21] op_sel_hi:[0,1]
	v_pk_mul_f32 v[22:23], v[40:41], v[22:23] op_sel_hi:[0,1]
	v_pk_mul_f32 v[16:17], v[40:41], v[16:17] op_sel_hi:[0,1]
	v_pk_mul_f32 v[18:19], v[40:41], v[18:19] op_sel_hi:[0,1]
	v_pk_mul_f32 v[22:23], v[30:31], v[22:23]
	v_pk_mul_f32 v[20:21], v[28:29], v[20:21]
	v_pk_mul_f32 v[26:27], v[26:27], v[18:19]
	v_pk_mul_f32 v[18:19], v[24:25], v[16:17]
	v_cvt_pk_bf16_f32 v16, v20, v21
	v_cvt_pk_bf16_f32 v17, v22, v23
	v_cvt_pk_bf16_f32 v18, v18, v19
	v_cvt_pk_bf16_f32 v19, v26, v27
	v_lshl_add_u64 v[36:37], v[136:137], 0, v[36:37]
	global_store_dwordx4 v[34:35], v[16:19], off
	s_nop 1
	v_mad_i64_i32 v[16:17], s[18:19], v32, s94, v[142:143]
	v_lshl_add_u64 v[16:17], v[16:17], 0, s[16:17]
	v_lshl_add_u64 v[16:17], v[16:17], 0, s[4:5]
	v_mov_b32_e32 v19, v231
	v_lshl_add_u64 v[16:17], v[16:17], 0, v[144:145]
	s_mov_b64 s[16:17], -1
	v_mul_f32_e32 v18, 0xbfb8aa3b, v19
	v_pk_mul_f32 v[6:7], v[6:7], v[18:19] op_sel_hi:[1,0]
	v_pk_mul_f32 v[4:5], v[4:5], v[18:19] op_sel_hi:[1,0]
	v_pk_mul_f32 v[2:3], v[2:3], v[18:19] op_sel_hi:[1,0]
	v_pk_mul_f32 v[0:1], v[0:1], v[18:19] op_sel_hi:[1,0]
	v_exp_f32_e32 v4, v4
	v_exp_f32_e32 v5, v5
	v_exp_f32_e32 v6, v6
	v_exp_f32_e32 v7, v7
	v_exp_f32_e32 v0, v0
	v_exp_f32_e32 v2, v2
	v_exp_f32_e32 v3, v3
	v_exp_f32_e32 v1, v1
	v_pk_add_f32 v[6:7], v[6:7], 1.0 op_sel_hi:[1,0]
	v_pk_add_f32 v[4:5], v[4:5], 1.0 op_sel_hi:[1,0]
	v_pk_add_f32 v[2:3], v[2:3], 1.0 op_sel_hi:[1,0]
	v_pk_add_f32 v[0:1], v[0:1], 1.0 op_sel_hi:[1,0]
	v_rcp_f32_e32 v4, v4
	v_rcp_f32_e32 v5, v5
	v_rcp_f32_e32 v6, v6
	v_rcp_f32_e32 v7, v7
	v_rcp_f32_e32 v0, v0
	v_rcp_f32_e32 v1, v1
	v_rcp_f32_e32 v2, v2
	v_rcp_f32_e32 v3, v3
	v_mul_f32_e32 v20, v19, v19
	v_pk_mul_f32 v[4:5], v[20:21], v[4:5] op_sel_hi:[0,1]
	v_pk_mul_f32 v[6:7], v[20:21], v[6:7] op_sel_hi:[0,1]
	v_pk_mul_f32 v[0:1], v[20:21], v[0:1] op_sel_hi:[0,1]
	v_pk_mul_f32 v[2:3], v[20:21], v[2:3] op_sel_hi:[0,1]
	v_pk_mul_f32 v[6:7], v[14:15], v[6:7]
	v_pk_mul_f32 v[4:5], v[12:13], v[4:5]
	v_pk_mul_f32 v[10:11], v[10:11], v[2:3]
	v_pk_mul_f32 v[2:3], v[8:9], v[0:1]
	v_cvt_pk_bf16_f32 v0, v4, v5
	v_cvt_pk_bf16_f32 v1, v6, v7
	v_cvt_pk_bf16_f32 v2, v2, v3
	v_cvt_pk_bf16_f32 v3, v10, v11
	global_store_dwordx4 v[16:17], v[0:3], off
	s_cbranch_vccnz .LBB0_707
	s_andn2_b64 vcc, exec, s[0:1]
	s_cbranch_vccnz .LBB0_706
	s_barrier
	s_branch .LBB0_706
